# K/V projection outputs written through (sc1) and the KV->X hand-off without an L2 write-back
# speedup vs baseline: 1.0133x; 1.0010x over previous
; DI unsigned pk2(float lo, float hi) { const f32x2 v = {lo, hi}; const bf16x2_t b = __builtin_convertvector(v, bf16x2_t); return __builtin_bit_cast(unsigned, b); }
; DI unsigned bf16_bits(float x) { return pk2(x, 0.f) & 0xffffu; }
; DI void unit_KV(const Params& p, char* lds, int l, int mtile, int q) {
;     ...
; #pragma unroll
;     for (int mt = 0; mt < 4; ++mt) {
;         const int r = mtile * 128 + wr * 64 + mt * 16 + l15, b = r >> 8, m = r & 255;
; #pragma unroll
;         for (int nt = 0; nt < 2; ++nt) {
;             const int col = 128 * q + wc * 32 + nt * 16 + quad * 4;
;             const f32x4 v = acc[mt][nt];
;             if (q < 2) {
;                 const int head = col >> 6, d = col & 63;
;                 *(u32x2*)(Kb + ((size_t)((b * 4 + head) * 256 + m)) * 64 + d) = (u32x2){pk2(v[0], v[1]), pk2(v[2], v[3])};
;             } else {
;                 const int cv = col - 256, head = cv >> 6, d = cv & 63;
;                 const int rr = m & 31, pos = (m & ~31) + 8 * ((rr >> 2) & 3) + 4 * (rr >> 4) + (rr & 3);
; #pragma unroll
;                 for (int i = 0; i < 4; ++i) Vp[((size_t)((b * 4 + head) * 64 + d + i)) * 256 + pos] = (bf16_t)bf16_bits(v[i]);
;             }
.Lpkv_join:
	s_lshl_b32 s14, s3, 7
	s_lshl_b32 s6, s6, 1
	v_readlane_b32 s7, v243, 12
	s_add_u32 s8, s7, s6
	v_readlane_b32 s7, v243, 13
	s_addc_u32 s9, s7, 0
	v_readlane_b32 s7, v243, 14
	v_ashrrev_i32_e32 v0, 2, v44
	s_add_u32 s10, s7, s6
	v_readlane_b32 s6, v243, 15
	v_and_b32_e32 v0, 0xffffffc0, v0
	s_addc_u32 s11, s6, 0
	v_lshl_add_u32 v34, s0, 7, v0
	v_lshrrev_b32_e32 v36, 1, v44
	v_lshrrev_b32_e32 v0, 2, v44
	v_and_b32_e32 v35, 0x60, v36
	v_and_b32_e32 v37, 12, v0
	s_cmp_gt_u32 s3, 1
	v_mov_b32_e32 v0, s14
	s_movk_i32 s3, 0x1c0
	v_lshlrev_b32_e32 v38, 1, v44
	v_and_b32_e32 v39, 3, v44
	v_and_b32_e32 v54, 0xc0, v34
	v_bitop3_b32 v0, v35, s3, v0 bitop3:0xc8
	v_and_or_b32 v55, v38, 24, v39
	v_and_b32_e32 v38, 0xffffff00, v34
	s_movk_i32 s3, 0xff00
	v_add3_u32 v45, v0, v38, s3
	v_or_b32_e32 v0, v54, v55
	v_lshlrev_b32_e32 v0, 1, v0
	v_lshl_add_u64 v[50:51], s[10:11], 0, v[0:1]
	v_and_or_b32 v0, v36, 32, v37
	s_cselect_b64 s[12:13], -1, 0
	v_or_b32_e32 v42, v45, v0
	s_mov_b64 s[6:7], -1
	s_and_b64 vcc, exec, s[12:13]
	v_ashrrev_i32_e32 v43, 31, v42
	v_or_b32_e32 v40, 1, v42
	v_or_b32_e32 v38, 2, v42
	v_or_b32_e32 v36, 3, v42
	s_waitcnt vmcnt(0)
	s_barrier
	s_cbranch_vccz .LBB0_864
	v_lshlrev_b64 v[46:47], 9, v[42:43]
	v_cvt_pk_bf16_f32 v37, v30, s0
	v_lshl_add_u64 v[46:47], v[50:51], 0, v[46:47]
	v_ashrrev_i32_e32 v41, 31, v40
	global_store_short v[46:47], v37, off sc1
	v_lshlrev_b64 v[46:47], 9, v[40:41]
	v_cvt_pk_bf16_f32 v37, v31, s0
	v_lshl_add_u64 v[46:47], v[50:51], 0, v[46:47]
	v_ashrrev_i32_e32 v39, 31, v38
	global_store_short v[46:47], v37, off sc1
	v_lshlrev_b64 v[46:47], 9, v[38:39]
	v_cvt_pk_bf16_f32 v37, v32, s0
	v_lshl_add_u64 v[46:47], v[50:51], 0, v[46:47]
	global_store_short v[46:47], v37, off sc1
	v_ashrrev_i32_e32 v37, 31, v36
	v_lshlrev_b64 v[46:47], 9, v[36:37]
	v_cvt_pk_bf16_f32 v39, v33, s0
	v_lshl_add_u64 v[46:47], v[50:51], 0, v[46:47]
	global_store_short v[46:47], v39, off sc1
	s_mov_b64 s[6:7], 0
.LBB0_864:
	v_or_b32_e32 v35, s14, v35
	v_lshrrev_b32_e32 v34, 6, v34
	v_lshrrev_b32_e32 v35, 6, v35
	v_and_b32_e32 v34, 0xfffffc, v34
	v_and_b32_e32 v37, 15, v44
	v_add_u32_e32 v34, v34, v35
	v_lshl_or_b32 v56, v34, 8, v37
	v_or_b32_e32 v48, v56, v54
	v_ashrrev_i32_e32 v49, 31, v48
	v_lshlrev_b64 v[34:35], 7, v[48:49]
	v_lshl_add_u64 v[52:53], s[8:9], 0, v[34:35]
	s_andn2_b64 vcc, exec, s[6:7]
	v_lshlrev_b32_e32 v34, 1, v0
	s_cbranch_vccnz .LBB0_866
	v_mov_b32_e32 v35, v1
	v_cvt_pk_bf16_f32 v30, v30, v31
	v_cvt_pk_bf16_f32 v31, v32, v33
	v_lshl_add_u64 v[32:33], v[52:53], 0, v[34:35]
	global_store_dwordx2 v[32:33], v[30:31], off sc1
.LBB0_866:
	v_or_b32_e32 v0, 16, v0
	v_cndmask_b32_e64 v30, 0, 1, s[12:13]
	v_or_b32_e32 v46, v0, v45
	s_mov_b64 s[14:15], -1
	v_cmp_ne_u32_e64 s[6:7], 1, v30
	s_andn2_b64 vcc, exec, s[12:13]
	v_ashrrev_i32_e32 v47, 31, v46
	v_or_b32_e32 v44, 1, v46
	v_or_b32_e32 v32, 2, v46
	v_or_b32_e32 v30, 3, v46
	s_cbranch_vccnz .LBB0_868
	v_lshlrev_b64 v[58:59], 9, v[46:47]
	v_cvt_pk_bf16_f32 v0, v26, s0
	v_lshl_add_u64 v[58:59], v[50:51], 0, v[58:59]
	v_ashrrev_i32_e32 v45, 31, v44
	global_store_short v[58:59], v0, off sc1
	v_lshlrev_b64 v[58:59], 9, v[44:45]
	v_cvt_pk_bf16_f32 v0, v27, s0
	v_lshl_add_u64 v[58:59], v[50:51], 0, v[58:59]
	v_ashrrev_i32_e32 v33, 31, v32
	global_store_short v[58:59], v0, off sc1
	v_lshlrev_b64 v[58:59], 9, v[32:33]
	v_cvt_pk_bf16_f32 v0, v28, s0
	v_lshl_add_u64 v[58:59], v[50:51], 0, v[58:59]
	v_ashrrev_i32_e32 v31, 31, v30
	global_store_short v[58:59], v0, off sc1
	v_lshlrev_b64 v[58:59], 9, v[30:31]
	v_cvt_pk_bf16_f32 v0, v29, s0
	v_lshl_add_u64 v[50:51], v[50:51], 0, v[58:59]
	s_mov_b64 s[14:15], 0
	global_store_short v[50:51], v0, off sc1
.LBB0_868:
	s_andn2_b64 vcc, exec, s[14:15]
	s_cbranch_vccnz .LBB0_870
	v_mov_b32_e32 v35, v1
	v_cvt_pk_bf16_f32 v26, v26, v27
	v_cvt_pk_bf16_f32 v27, v28, v29
	v_lshl_add_u64 v[28:29], v[52:53], 0, v[34:35]
	global_store_dwordx2 v[28:29], v[26:27], off offset:32 sc1
.LBB0_870:
	v_add_lshl_u32 v0, v55, v54, 1
	v_lshl_add_u64 v[26:27], s[10:11], 0, v[0:1]
	s_and_b64 vcc, exec, s[6:7]
	s_mov_b64 s[12:13], -1
	s_cbranch_vccnz .LBB0_872
	v_lshlrev_b64 v[28:29], 9, v[42:43]
	v_cvt_pk_bf16_f32 v0, v22, s0
	v_lshl_add_u64 v[28:29], v[26:27], 0, v[28:29]
	v_ashrrev_i32_e32 v41, 31, v40
	global_store_short v[28:29], v0, off offset:8 sc1
	v_lshlrev_b64 v[28:29], 9, v[40:41]
	v_cvt_pk_bf16_f32 v0, v23, s0
	v_lshl_add_u64 v[28:29], v[26:27], 0, v[28:29]
	v_ashrrev_i32_e32 v39, 31, v38
	global_store_short v[28:29], v0, off offset:8 sc1
	v_lshlrev_b64 v[28:29], 9, v[38:39]
	v_cvt_pk_bf16_f32 v0, v24, s0
	v_lshl_add_u64 v[28:29], v[26:27], 0, v[28:29]
	v_ashrrev_i32_e32 v37, 31, v36
	global_store_short v[28:29], v0, off offset:8 sc1
	v_lshlrev_b64 v[28:29], 9, v[36:37]
	v_cvt_pk_bf16_f32 v0, v25, s0
	v_lshl_add_u64 v[28:29], v[26:27], 0, v[28:29]
	s_mov_b64 s[12:13], 0
	global_store_short v[28:29], v0, off offset:8 sc1

; DI unsigned bf16_bits(float x) { return pk2(x, 0.f) & 0xffffu; }
; DI void unit_KV(const Params& p, char* lds, int l, int mtile, int q) {
;     ...
;                 const int cv = col - 256, head = cv >> 6, d = cv & 63;
;                 const int rr = m & 31, pos = (m & ~31) + 8 * ((rr >> 2) & 3) + 4 * (rr >> 4) + (rr & 3);
; #pragma unroll
;                 for (int i = 0; i < 4; ++i) Vp[((size_t)((b * 4 + head) * 64 + d + i)) * 256 + pos] = (bf16_t)bf16_bits(v[i]);
.LBB0_876:
	v_lshlrev_b64 v[18:19], 9, v[42:43]
	v_cvt_pk_bf16_f32 v0, v14, s0
	v_lshl_add_u64 v[18:19], v[26:27], 0, v[18:19]
	v_ashrrev_i32_e32 v41, 31, v40
	global_store_short v[18:19], v0, off offset:64 sc1
	v_lshlrev_b64 v[18:19], 9, v[40:41]
	v_cvt_pk_bf16_f32 v0, v15, s0
	v_lshl_add_u64 v[18:19], v[26:27], 0, v[18:19]
	v_ashrrev_i32_e32 v39, 31, v38
	global_store_short v[18:19], v0, off offset:64 sc1
	v_lshlrev_b64 v[18:19], 9, v[38:39]
	v_cvt_pk_bf16_f32 v0, v16, s0
	v_lshl_add_u64 v[18:19], v[26:27], 0, v[18:19]
	v_ashrrev_i32_e32 v37, 31, v36
	global_store_short v[18:19], v0, off offset:64 sc1
	v_lshlrev_b64 v[18:19], 9, v[36:37]
	v_cvt_pk_bf16_f32 v0, v17, s0
	v_lshl_add_u64 v[18:19], v[26:27], 0, v[18:19]
	s_mov_b64 s[12:13], 0
	global_store_short v[18:19], v0, off offset:64 sc1

; DI unsigned pk2(float lo, float hi) { const f32x2 v = {lo, hi}; const bf16x2_t b = __builtin_convertvector(v, bf16x2_t); return __builtin_bit_cast(unsigned, b); }
; DI unsigned bf16_bits(float x) { return pk2(x, 0.f) & 0xffffu; }
; DI void unit_KV(const Params& p, char* lds, int l, int mtile, int q) {
;     ...
;             const int col = 128 * q + wc * 32 + nt * 16 + quad * 4;
;             const f32x4 v = acc[mt][nt];
;             if (q < 2) {
;                 const int head = col >> 6, d = col & 63;
;                 *(u32x2*)(Kb + ((size_t)((b * 4 + head) * 256 + m)) * 64 + d) = (u32x2){pk2(v[0], v[1]), pk2(v[2], v[3])};
;             } else {
;                 const int cv = col - 256, head = cv >> 6, d = cv & 63;
;                 const int rr = m & 31, pos = (m & ~31) + 8 * ((rr >> 2) & 3) + 4 * (rr >> 4) + (rr & 3);
; #pragma unroll
;                 for (int i = 0; i < 4; ++i) Vp[((size_t)((b * 4 + head) * 64 + d + i)) * 256 + pos] = (bf16_t)bf16_bits(v[i]);
.LBB0_880:
	v_mov_b32_e32 v35, v1
	v_cvt_pk_bf16_f32 v10, v10, v11
	v_cvt_pk_bf16_f32 v11, v12, v13
	v_lshl_add_u64 v[12:13], v[18:19], 0, v[34:35]
	global_store_dwordx2 v[12:13], v[10:11], off offset:32 sc1
.LBB0_881:
	v_add_u32_e32 v0, v54, v55
	v_lshl_add_u32 v0, v0, 1, 8
	v_lshl_add_u64 v[10:11], s[10:11], 0, v[0:1]
	s_and_b64 vcc, exec, s[6:7]
	s_mov_b64 s[10:11], -1
	s_cbranch_vccnz .LBB0_883
	v_lshlrev_b64 v[12:13], 9, v[42:43]
	v_cvt_pk_bf16_f32 v0, v6, s0
	v_lshl_add_u64 v[12:13], v[10:11], 0, v[12:13]
	v_ashrrev_i32_e32 v41, 31, v40
	global_store_short v[12:13], v0, off offset:64 sc1
	v_lshlrev_b64 v[12:13], 9, v[40:41]
	v_cvt_pk_bf16_f32 v0, v7, s0
	v_lshl_add_u64 v[12:13], v[10:11], 0, v[12:13]
	v_ashrrev_i32_e32 v39, 31, v38
	global_store_short v[12:13], v0, off offset:64 sc1
	v_lshlrev_b64 v[12:13], 9, v[38:39]
	v_cvt_pk_bf16_f32 v0, v8, s0
	v_lshl_add_u64 v[12:13], v[10:11], 0, v[12:13]
	v_ashrrev_i32_e32 v37, 31, v36
	global_store_short v[12:13], v0, off offset:64 sc1
	v_lshlrev_b64 v[12:13], 9, v[36:37]
	v_cvt_pk_bf16_f32 v0, v9, s0
	v_lshl_add_u64 v[12:13], v[10:11], 0, v[12:13]
	s_mov_b64 s[10:11], 0
	global_store_short v[12:13], v0, off offset:64 sc1

; DI unsigned pk2(float lo, float hi) { const f32x2 v = {lo, hi}; const bf16x2_t b = __builtin_convertvector(v, bf16x2_t); return __builtin_bit_cast(unsigned, b); }
; DI void unit_KV(const Params& p, char* lds, int l, int mtile, int q) {
;     ...
;                 *(u32x2*)(Kb + ((size_t)((b * 4 + head) * 256 + m)) * 64 + d) = (u32x2){pk2(v[0], v[1]), pk2(v[2], v[3])};
.LBB0_886:
	v_mov_b32_e32 v35, v1
	v_cvt_pk_bf16_f32 v2, v2, v3
	v_cvt_pk_bf16_f32 v3, v4, v5
	v_lshl_add_u64 v[4:5], v[12:13], 0, v[34:35]
	global_store_dwordx2 v[4:5], v[2:3], off offset:32 sc1

; template <int N> DI void wait_vm() { asm volatile("s_waitcnt vmcnt(%0)" ::"n"(N) : "memory"); }
; DI void signal_done(unsigned* c) {
;     wait_vm<0>();
;     __syncthreads();
;     if (threadIdx.x == 0) { __builtin_amdgcn_fence(__ATOMIC_RELEASE, "agent"); __hip_atomic_fetch_add(c, 1u, __ATOMIC_RELAXED, __HIP_MEMORY_SCOPE_AGENT); }
; }
.Lcen_kv_done:
	v_add_u32_e32 v23, 0x1c0, v2
	v_mov_b32_e32 v24, 0x34c
	global_atomic_add v0, v23, v3, s[10:11] sc0
	s_waitcnt vmcnt(0)
	v_readfirstlane_b32 s9, v0
	s_nop 3
	s_add_u32 s9, s9, 1
	s_cmp_eq_u32 s9, s8
	s_cbranch_scc0 .LBB0_890
	global_atomic_add v24, v3, s[10:11]

; DI unsigned pk2(float lo, float hi) { const f32x2 v = {lo, hi}; const bf16x2_t b = __builtin_convertvector(v, bf16x2_t); return __builtin_bit_cast(unsigned, b); }
; DI unsigned bf16_bits(float x) { return pk2(x, 0.f) & 0xffffu; }
; DI void unit_KV(const Params& p, char* lds, int l, int mtile, int q) {
;     ...
;     for (int mt = 0; mt < 4; ++mt) {
;         const int r = mtile * 128 + wr * 64 + mt * 16 + l15, b = r >> 8, m = r & 255;
; #pragma unroll
;         for (int nt = 0; nt < 2; ++nt) {
;             const int col = 128 * q + wc * 32 + nt * 16 + quad * 4;
;             const f32x4 v = acc[mt][nt];
;             if (q < 2) {
;                 const int head = col >> 6, d = col & 63;
;                 *(u32x2*)(Kb + ((size_t)((b * 4 + head) * 256 + m)) * 64 + d) = (u32x2){pk2(v[0], v[1]), pk2(v[2], v[3])};
;             } else {
;                 const int cv = col - 256, head = cv >> 6, d = cv & 63;
;                 const int rr = m & 31, pos = (m & ~31) + 8 * ((rr >> 2) & 3) + 4 * (rr >> 4) + (rr & 3);
; #pragma unroll
;                 for (int i = 0; i < 4; ++i) Vp[((size_t)((b * 4 + head) * 64 + d + i)) * 256 + pos] = (bf16_t)bf16_bits(v[i]);
.LBB0_1026:
	v_mov_b32_e32 v35, v1
	v_cvt_pk_bf16_f32 v22, v22, v23
	v_cvt_pk_bf16_f32 v23, v24, v25
	v_lshl_add_u64 v[24:25], v[28:29], 0, v[34:35]
	global_store_dwordx2 v[24:25], v[22:23], off sc1
	s_and_b64 vcc, exec, s[6:7]
	s_mov_b64 s[12:13], -1
	s_cbranch_vccnz .LBB0_874
.LBB0_1027:
	v_lshlrev_b64 v[22:23], 9, v[46:47]
	v_cvt_pk_bf16_f32 v0, v18, s0
	v_lshl_add_u64 v[22:23], v[26:27], 0, v[22:23]
	v_ashrrev_i32_e32 v45, 31, v44
	global_store_short v[22:23], v0, off offset:8 sc1
	v_lshlrev_b64 v[22:23], 9, v[44:45]
	v_cvt_pk_bf16_f32 v0, v19, s0
	v_lshl_add_u64 v[22:23], v[26:27], 0, v[22:23]
	v_ashrrev_i32_e32 v33, 31, v32
	global_store_short v[22:23], v0, off offset:8 sc1
	v_lshlrev_b64 v[22:23], 9, v[32:33]
	v_cvt_pk_bf16_f32 v0, v20, s0
	v_lshl_add_u64 v[22:23], v[26:27], 0, v[22:23]
	v_ashrrev_i32_e32 v31, 31, v30
	global_store_short v[22:23], v0, off offset:8 sc1
	v_lshlrev_b64 v[22:23], 9, v[30:31]
	v_cvt_pk_bf16_f32 v0, v21, s0
	v_lshl_add_u64 v[22:23], v[26:27], 0, v[22:23]
	global_store_short v[22:23], v0, off offset:8 sc1
	s_cbranch_execnz .LBB0_875
.LBB0_1028:
	v_mov_b32_e32 v35, v1
	v_cvt_pk_bf16_f32 v18, v18, v19
	v_cvt_pk_bf16_f32 v19, v20, v21
	v_lshl_add_u64 v[20:21], v[28:29], 0, v[34:35]
	global_store_dwordx2 v[20:21], v[18:19], off offset:32 sc1
	s_and_b64 vcc, exec, s[6:7]
	s_mov_b64 s[12:13], -1
	s_cbranch_vccz .LBB0_876
	s_branch .LBB0_877
.LBB0_1029:
	v_mov_b32_e32 v35, v1
	v_cvt_pk_bf16_f32 v14, v14, v15
	v_cvt_pk_bf16_f32 v15, v16, v17
	v_lshl_add_u64 v[16:17], v[18:19], 0, v[34:35]
	global_store_dwordx2 v[16:17], v[14:15], off sc1
	s_and_b64 vcc, exec, s[6:7]
	s_mov_b64 s[12:13], -1
	s_cbranch_vccnz .LBB0_879
.LBB0_1030:
	v_lshlrev_b64 v[14:15], 9, v[46:47]
	v_cvt_pk_bf16_f32 v0, v10, s0
	v_lshl_add_u64 v[14:15], v[26:27], 0, v[14:15]
	v_ashrrev_i32_e32 v45, 31, v44
	global_store_short v[14:15], v0, off offset:64 sc1
	v_lshlrev_b64 v[14:15], 9, v[44:45]
	v_cvt_pk_bf16_f32 v0, v11, s0
	v_lshl_add_u64 v[14:15], v[26:27], 0, v[14:15]
	v_ashrrev_i32_e32 v33, 31, v32
	global_store_short v[14:15], v0, off offset:64 sc1
	v_lshlrev_b64 v[14:15], 9, v[32:33]
	v_cvt_pk_bf16_f32 v0, v12, s0
	v_lshl_add_u64 v[14:15], v[26:27], 0, v[14:15]
	v_ashrrev_i32_e32 v31, 31, v30
	global_store_short v[14:15], v0, off offset:64 sc1
	v_lshlrev_b64 v[14:15], 9, v[30:31]
	v_cvt_pk_bf16_f32 v0, v13, s0
	v_lshl_add_u64 v[14:15], v[26:27], 0, v[14:15]
	global_store_short v[14:15], v0, off offset:64 sc1
	s_cbranch_execz .LBB0_880
	s_branch .LBB0_881
.LBB0_1031:
	v_mov_b32_e32 v35, v1
	v_cvt_pk_bf16_f32 v6, v6, v7
	v_cvt_pk_bf16_f32 v7, v8, v9
	v_lshl_add_u64 v[8:9], v[12:13], 0, v[34:35]
	global_store_dwordx2 v[8:9], v[6:7], off sc1
	s_and_b64 vcc, exec, s[6:7]
	s_mov_b64 s[6:7], -1
	s_cbranch_vccnz .LBB0_885
.LBB0_1032:
	v_lshlrev_b64 v[6:7], 9, v[46:47]
	v_cvt_pk_bf16_f32 v0, v2, s0
	v_lshl_add_u64 v[6:7], v[10:11], 0, v[6:7]
	v_ashrrev_i32_e32 v45, 31, v44
	global_store_short v[6:7], v0, off offset:64 sc1
	v_lshlrev_b64 v[6:7], 9, v[44:45]
	v_cvt_pk_bf16_f32 v0, v3, s0
	v_lshl_add_u64 v[6:7], v[10:11], 0, v[6:7]
	v_ashrrev_i32_e32 v33, 31, v32
	global_store_short v[6:7], v0, off offset:64 sc1
	v_lshlrev_b64 v[6:7], 9, v[32:33]
	v_cvt_pk_bf16_f32 v0, v4, s0
	v_lshl_add_u64 v[6:7], v[10:11], 0, v[6:7]
	v_ashrrev_i32_e32 v31, 31, v30
	global_store_short v[6:7], v0, off offset:64 sc1
	v_lshlrev_b64 v[6:7], 9, v[30:31]
	v_cvt_pk_bf16_f32 v0, v5, s0
	v_lshl_add_u64 v[6:7], v[10:11], 0, v[6:7]
	global_store_short v[6:7], v0, off offset:64 sc1
	s_cbranch_execz .LBB0_886
	s_branch .LBB0_887
